# lever 7.3: attention unit epilogue stores widened, 8 dwordx2 -> 4 dwordx4 via v_permlane32_swap pairs (on top of v40)
# speedup vs baseline: 1.0059x; 1.0045x over previous
.LBB0_870:
	v_lshl_add_u64 v[30:31], s[96:97], 1, v[30:31]
	v_and_b32_e32 v35, 32, v211
	v_lshrrev_b32_e32 v35, 2, v35
	v_lshl_add_u32 v34, v138, 1, v35
	v_mov_b32_e32 v35, v151
	v_lshl_add_u64 v[30:31], v[30:31], 0, v[34:35]
	v_cvt_pk_bf16_f32 v36, v32, v33
	v_cvt_pk_bf16_f32 v37, v16, v17
	v_cvt_pk_bf16_f32 v38, v18, v19
	v_cvt_pk_bf16_f32 v39, v20, v21
	v_cvt_pk_bf16_f32 v40, v22, v23
	v_cvt_pk_bf16_f32 v41, v24, v25
	v_cvt_pk_bf16_f32 v42, v26, v27
	v_cvt_pk_bf16_f32 v43, v28, v29
	v_readlane_b32 s2, v240, 24
	v_permlane32_swap_b32_e32 v36, v38
	v_permlane32_swap_b32_e32 v37, v39
	v_cvt_pk_bf16_f32 v44, v0, v1
	v_cvt_pk_bf16_f32 v45, v2, v3
	global_store_dwordx4 v[30:31], v[36:39], off
	v_cvt_pk_bf16_f32 v46, v4, v5
	v_cvt_pk_bf16_f32 v47, v6, v7
	v_readlane_b32 s3, v240, 25
	v_permlane32_swap_b32_e32 v40, v42
	v_permlane32_swap_b32_e32 v41, v43
	v_cvt_pk_bf16_f32 v48, v8, v9
	v_cvt_pk_bf16_f32 v49, v10, v11
	global_store_dwordx4 v[30:31], v[40:43], off offset:32
	v_cvt_pk_bf16_f32 v50, v12, v13
	v_cvt_pk_bf16_f32 v51, v14, v15
	v_readlane_b32 s14, v240, 15
	v_readlane_b32 s55, v240, 20
	v_permlane32_swap_b32_e32 v44, v46
	v_permlane32_swap_b32_e32 v45, v47
	global_store_dwordx4 v[30:31], v[44:47], off offset:64
	s_nop 1
	v_permlane32_swap_b32_e32 v48, v50
	v_permlane32_swap_b32_e32 v49, v51
	global_store_dwordx4 v[30:31], v[48:51], off offset:96
